# plus attention finish: sub-layer gain loads hoisted, no per-store waits
# speedup vs baseline: 1.0022x; 1.0022x over previous
.LBB0_378:
	s_setprio 0
	ds_bpermute_b32 v0, v127, v114
	ds_bpermute_b32 v1, v127, v115
	s_waitcnt vmcnt(0)
	s_waitcnt lgkmcnt(0)
	v_pk_add_f32 v[0:1], v[114:115], v[0:1]
	ds_bpermute_b32 v2, v128, v0
	ds_bpermute_b32 v3, v128, v1
	s_waitcnt lgkmcnt(0)
	v_pk_add_f32 v[0:1], v[0:1], v[2:3]
	s_nop 0
	v_div_scale_f32 v2, s[0:1], v1, v1, v101
	v_rcp_f32_e32 v3, v2
	s_nop 0
	v_fma_f32 v4, -v2, v3, 1.0
	v_fmac_f32_e32 v3, v4, v3
	v_div_scale_f32 v4, vcc, v101, v1, v101
	v_mul_f32_e32 v5, v4, v3
	v_fma_f32 v6, -v2, v5, v4
	v_fmac_f32_e32 v5, v6, v3
	v_fma_f32 v2, -v2, v5, v4
	v_div_fmas_f32 v2, v2, v3, v5
	v_div_fixup_f32 v1, v2, v1, v101
	v_div_scale_f32 v2, s[0:1], v0, v0, 1.0
	v_rcp_f32_e32 v3, v2
	s_load_dwordx2 s[0:1], s[28:29], 0x58
	v_fma_f32 v4, -v2, v3, 1.0
	v_fmac_f32_e32 v3, v4, v3
	v_div_scale_f32 v4, vcc, 1.0, v0, 1.0
	v_mul_f32_e32 v5, v4, v3
	v_fma_f32 v6, -v2, v5, v4
	v_fmac_f32_e32 v5, v6, v3
	v_fma_f32 v2, -v2, v5, v4
	v_div_fmas_f32 v2, v2, v3, v5
	v_div_fixup_f32 v0, v2, v0, 1.0
	v_pk_mul_f32 v[2:3], v[0:1], v[124:125]
	s_waitcnt lgkmcnt(0)
	s_add_u32 s0, s0, s37
	v_sub_f32_e32 v56, v2, v3
	v_pk_mul_f32 v[2:3], v[0:1], v[48:49]
	s_addc_u32 s1, s1, 0
	v_sub_f32_e32 v57, v2, v3
	v_pk_mul_f32 v[2:3], v[0:1], v[122:123]
	v_lshl_add_u64 v[8:9], v[104:105], 2, s[0:1]
	v_sub_f32_e32 v58, v2, v3
	v_pk_mul_f32 v[2:3], v[0:1], v[50:51]
	s_nop 0
	v_sub_f32_e32 v51, v2, v3
	v_pk_mul_f32 v[2:3], v[0:1], v[120:121]
	s_nop 0
	v_sub_f32_e32 v50, v2, v3
	v_pk_mul_f32 v[2:3], v[0:1], v[44:45]
	s_nop 0
	v_sub_f32_e32 v49, v2, v3
	v_pk_mul_f32 v[2:3], v[0:1], v[118:119]
	s_nop 0
	v_sub_f32_e32 v48, v2, v3
	v_pk_mul_f32 v[2:3], v[0:1], v[46:47]
	s_nop 0
	v_sub_f32_e32 v47, v2, v3
	v_pk_mul_f32 v[2:3], v[0:1], v[116:117]
	s_nop 0
	v_sub_f32_e32 v46, v2, v3
	v_pk_mul_f32 v[2:3], v[0:1], v[40:41]
	s_nop 0
	v_sub_f32_e32 v45, v2, v3
	v_pk_mul_f32 v[2:3], v[0:1], v[98:99]
	s_nop 0
	v_sub_f32_e32 v44, v2, v3
	v_pk_mul_f32 v[2:3], v[0:1], v[42:43]
	s_nop 0
	v_sub_f32_e32 v43, v2, v3
	v_pk_mul_f32 v[2:3], v[0:1], v[96:97]
	s_nop 0
	v_sub_f32_e32 v42, v2, v3
	v_pk_mul_f32 v[2:3], v[0:1], v[36:37]
	s_nop 0
	v_sub_f32_e32 v41, v2, v3
	v_pk_mul_f32 v[2:3], v[0:1], v[94:95]
	s_nop 0
	v_sub_f32_e32 v40, v2, v3
	v_pk_mul_f32 v[2:3], v[0:1], v[38:39]
	s_nop 0
	v_sub_f32_e32 v39, v2, v3
	v_pk_mul_f32 v[2:3], v[0:1], v[92:93]
	s_nop 0
	v_sub_f32_e32 v38, v2, v3
	v_pk_mul_f32 v[2:3], v[0:1], v[32:33]
	s_nop 0
	v_sub_f32_e32 v37, v2, v3
	v_pk_mul_f32 v[2:3], v[0:1], v[90:91]
	s_nop 0
	v_sub_f32_e32 v36, v2, v3
	v_pk_mul_f32 v[2:3], v[0:1], v[34:35]
	s_nop 0
	v_sub_f32_e32 v33, v2, v3
	v_pk_mul_f32 v[2:3], v[0:1], v[88:89]
	s_nop 0
	v_sub_f32_e32 v32, v2, v3
	v_pk_mul_f32 v[2:3], v[0:1], v[24:25]
	s_nop 0
	v_sub_f32_e32 v29, v2, v3
	v_pk_mul_f32 v[2:3], v[0:1], v[86:87]
	s_nop 0
	v_sub_f32_e32 v28, v2, v3
	v_pk_mul_f32 v[2:3], v[0:1], v[26:27]
	s_nop 0
	v_sub_f32_e32 v25, v2, v3
	v_pk_mul_f32 v[2:3], v[0:1], v[84:85]
	s_nop 0
	v_sub_f32_e32 v24, v2, v3
	v_pk_mul_f32 v[2:3], v[0:1], v[20:21]
	s_nop 0
	v_sub_f32_e32 v15, v2, v3
	v_pk_mul_f32 v[2:3], v[0:1], v[54:55]
	s_nop 0
	v_sub_f32_e32 v14, v2, v3
	v_pk_mul_f32 v[2:3], v[0:1], v[22:23]
	s_nop 0
	v_sub_f32_e32 v12, v2, v3
	v_pk_mul_f32 v[2:3], v[0:1], v[52:53]
	s_nop 0
	v_sub_f32_e32 v11, v2, v3
	v_pk_mul_f32 v[2:3], v[0:1], v[16:17]
	s_nop 0
	v_sub_f32_e32 v10, v2, v3
	v_mov_b32_e32 v2, v1
	v_pk_mul_f32 v[2:3], v[2:3], v[18:19] op_sel_hi:[0,1]
	v_pk_fma_f32 v[4:5], v[0:1], v[30:31], v[2:3] op_sel_hi:[0,1,1] neg_lo:[0,0,1] neg_hi:[0,0,1]
	v_mul_f32_e32 v2, v56, v56
	v_fmac_f32_e32 v2, v57, v57
	v_fmac_f32_e32 v2, v58, v58
	v_fmac_f32_e32 v2, v51, v51
	v_fmac_f32_e32 v2, v50, v50
	v_fmac_f32_e32 v2, v49, v49
	v_fmac_f32_e32 v2, v48, v48
	v_fmac_f32_e32 v2, v47, v47
	v_fmac_f32_e32 v2, v46, v46
	v_fmac_f32_e32 v2, v45, v45
	v_fmac_f32_e32 v2, v44, v44
	v_fmac_f32_e32 v2, v43, v43
	v_fmac_f32_e32 v2, v42, v42
	v_fmac_f32_e32 v2, v41, v41
	v_fmac_f32_e32 v2, v40, v40
	v_fmac_f32_e32 v2, v39, v39
	v_fmac_f32_e32 v2, v38, v38
	v_fmac_f32_e32 v2, v37, v37
	v_fmac_f32_e32 v2, v36, v36
	v_fmac_f32_e32 v2, v33, v33
	v_fmac_f32_e32 v2, v32, v32
	v_fmac_f32_e32 v2, v29, v29
	v_fmac_f32_e32 v2, v28, v28
	v_fmac_f32_e32 v2, v25, v25
	v_fmac_f32_e32 v2, v24, v24
	v_fmac_f32_e32 v2, v15, v15
	v_fmac_f32_e32 v2, v14, v14
	v_fmac_f32_e32 v2, v12, v12
	v_fmac_f32_e32 v2, v11, v11
	v_pk_mul_f32 v[0:1], v[4:5], v[4:5]
	v_fmac_f32_e32 v2, v10, v10
	v_add_f32_e32 v0, v2, v0
	v_add_f32_e32 v0, v0, v1
	ds_bpermute_b32 v1, v127, v0
	s_waitcnt lgkmcnt(0)
	v_add_f32_e32 v0, v0, v1
	ds_bpermute_b32 v1, v128, v0
	s_waitcnt lgkmcnt(0)
	v_add_f32_e32 v0, v0, v1
	v_fmamk_f32 v0, v0, 0x3c000000, v213
	v_rsq_f32_e32 v0, v0
	s_nop 0
	v_mul_f32_e32 v13, v134, v0
	v_lshlrev_b64 v[0:1], 11, v[140:141]
	v_lshl_add_u64 v[0:1], s[22:23], 0, v[0:1]
	v_lshl_add_u64 v[0:1], s[52:53], 1, v[0:1]
	v_lshl_add_u64 v[6:7], v[104:105], 1, v[0:1]
	global_load_dwordx4 v[160:163], v[8:9], off
	global_load_dwordx4 v[164:167], v[8:9], off offset:64
	global_load_dwordx4 v[168:171], v[8:9], off offset:128
	global_load_dwordx4 v[172:175], v[8:9], off offset:192
	global_load_dwordx4 v[176:179], v[8:9], off offset:256
	global_load_dwordx4 v[180:183], v[8:9], off offset:320
	global_load_dwordx4 v[184:187], v[8:9], off offset:384
	global_load_dwordx4 v[188:191], v[8:9], off offset:448
	v_mul_f32_e32 v16, v13, v56
	v_mul_f32_e32 v15, v13, v15
	s_waitcnt vmcnt(0)
	v_mov_b64_e32 v[0:1], v[160:161]
	v_mov_b64_e32 v[2:3], v[162:163]
	v_mul_f32_e32 v0, v0, v16
	v_mul_f32_e32 v16, v13, v57
	v_mul_f32_e32 v1, v1, v16
	v_cvt_pk_bf16_f32 v0, v0, v1
	v_mul_f32_e32 v1, v13, v58
	v_mul_f32_e32 v1, v2, v1
	v_mul_f32_e32 v2, v13, v51
	v_mul_f32_e32 v2, v3, v2
	v_cvt_pk_bf16_f32 v1, v1, v2
	flat_store_dwordx2 v[6:7], v[0:1]
	v_mov_b64_e32 v[0:1], v[164:165]
	v_mov_b64_e32 v[2:3], v[166:167]
	v_mul_f32_e32 v16, v13, v50
	v_mul_f32_e32 v0, v0, v16
	v_mul_f32_e32 v16, v13, v49
	v_mul_f32_e32 v1, v1, v16
	v_cvt_pk_bf16_f32 v0, v0, v1
	v_mul_f32_e32 v1, v13, v48
	v_mul_f32_e32 v1, v2, v1
	v_mul_f32_e32 v2, v13, v47
	v_mul_f32_e32 v2, v3, v2
	v_cvt_pk_bf16_f32 v1, v1, v2
	flat_store_dwordx2 v[6:7], v[0:1] offset:32
	v_mov_b64_e32 v[0:1], v[168:169]
	v_mov_b64_e32 v[2:3], v[170:171]
	v_mul_f32_e32 v16, v13, v46
	v_mul_f32_e32 v0, v0, v16
	v_mul_f32_e32 v16, v13, v45
	v_mul_f32_e32 v1, v1, v16
	v_cvt_pk_bf16_f32 v0, v0, v1
	v_mul_f32_e32 v1, v13, v44
	v_mul_f32_e32 v1, v2, v1
	v_mul_f32_e32 v2, v13, v43
	v_mul_f32_e32 v2, v3, v2
	v_cvt_pk_bf16_f32 v1, v1, v2
	flat_store_dwordx2 v[6:7], v[0:1] offset:64
	v_mov_b64_e32 v[0:1], v[172:173]
	v_mov_b64_e32 v[2:3], v[174:175]
	v_mul_f32_e32 v16, v13, v42
	v_mul_f32_e32 v0, v0, v16
	v_mul_f32_e32 v16, v13, v41
	v_mul_f32_e32 v1, v1, v16
	v_cvt_pk_bf16_f32 v0, v0, v1
	v_mul_f32_e32 v1, v13, v40
	v_mul_f32_e32 v1, v2, v1
	v_mul_f32_e32 v2, v13, v39
	v_mul_f32_e32 v2, v3, v2
	v_cvt_pk_bf16_f32 v1, v1, v2
	flat_store_dwordx2 v[6:7], v[0:1] offset:96
	v_mov_b64_e32 v[0:1], v[176:177]
	v_mov_b64_e32 v[2:3], v[178:179]
	v_mul_f32_e32 v16, v13, v38
	v_mul_f32_e32 v0, v0, v16
	v_mul_f32_e32 v16, v13, v37
	v_mul_f32_e32 v1, v1, v16
	v_cvt_pk_bf16_f32 v0, v0, v1
	v_mul_f32_e32 v1, v13, v36
	v_mul_f32_e32 v1, v2, v1
	v_mul_f32_e32 v2, v13, v33
	v_mul_f32_e32 v2, v3, v2
	v_cvt_pk_bf16_f32 v1, v1, v2
	flat_store_dwordx2 v[6:7], v[0:1] offset:128
	v_mov_b64_e32 v[0:1], v[180:181]
	v_mov_b64_e32 v[2:3], v[182:183]
	v_mul_f32_e32 v16, v13, v32
	v_mul_f32_e32 v0, v0, v16
	v_mul_f32_e32 v16, v13, v29
	v_mul_f32_e32 v1, v1, v16
	v_cvt_pk_bf16_f32 v0, v0, v1
	v_mul_f32_e32 v1, v13, v28
	v_mul_f32_e32 v1, v2, v1
	v_mul_f32_e32 v2, v13, v25
	v_mul_f32_e32 v2, v3, v2
	v_cvt_pk_bf16_f32 v1, v1, v2
	flat_store_dwordx2 v[6:7], v[0:1] offset:160
	v_mov_b64_e32 v[0:1], v[184:185]
	v_mov_b64_e32 v[2:3], v[186:187]
	v_mul_f32_e32 v16, v13, v24
	v_mul_f32_e32 v0, v0, v16
	v_mul_f32_e32 v1, v1, v15
	v_cvt_pk_bf16_f32 v0, v0, v1
	v_mul_f32_e32 v1, v13, v14
	v_mul_f32_e32 v1, v2, v1
	v_mul_f32_e32 v2, v13, v12
	v_mul_f32_e32 v2, v3, v2
	v_cvt_pk_bf16_f32 v1, v1, v2
	flat_store_dwordx2 v[6:7], v[0:1] offset:192
	v_mov_b64_e32 v[0:1], v[188:189]
	v_mov_b64_e32 v[2:3], v[190:191]
	v_mul_f32_e32 v8, v13, v11
	v_mul_f32_e32 v0, v0, v8
	v_mul_f32_e32 v8, v13, v10
	v_mul_f32_e32 v1, v1, v8
	v_cvt_pk_bf16_f32 v0, v0, v1
	v_mul_f32_e32 v1, v13, v4
	v_mul_f32_e32 v1, v2, v1
	v_mul_f32_e32 v2, v13, v5
	v_mul_f32_e32 v2, v3, v2
	v_cvt_pk_bf16_f32 v1, v1, v2
	flat_store_dwordx2 v[6:7], v[0:1] offset:224
	s_waitcnt lgkmcnt(0)
	s_barrier
	s_and_saveexec_b64 s[0:1], s[6:7]
	s_cbranch_execz .LBB0_351
	v_readlane_b32 s2, v253, 44
	s_nop 1
	v_mov_b32_e32 v0, s2
	ds_write_b32 v0, v156
	s_branch .LBB0_351
